# attention items: the 32 bias look-ups per key tile are plain LDS reads issued ahead of each 16-key group's K reads + v_cndmask (was 32 exec-masked branches each with its own ds_read + lgkmcnt(0))
# speedup vs baseline: 1.0063x; 1.0063x over previous
; #define ATT_ISSUE(kt_) do { const int ktn_ = (kt_); ATT_LD(0, pk0, pv0); ATT_LD(1, pk1, pv1); ATT_LD(2, pk2_, pv2); ATT_LD(3, pk3, pv3); } while (0)
; #define ATT_ST(i, RK, RV) do { const int q = tid + NTHR * (i), row = q >> 4, c16 = q & 15; \
;       *(uint4*)(Ks + row * LDP + c16 * 8) = RK; *(uint4*)(Vs + row * LDV + c16 * 8) = RV; } while (0)
; __device__ __forceinline__ void attn_item(const Params& P, const int pass, const int item, const int wvi) {
;     ...
;   for (int kt = kt_lo; kt <= kt_hi; ++kt) {
;     u16* Ks = (u16*)(smem + (kt & 1) * ATT_SET);
;     u16* Vs = Ks + 128 * LDP;
;     ATT_ST(0, pk0, pv0); ATT_ST(1, pk1, pv1); ATT_ST(2, pk2_, pv2); ATT_ST(3, pk3, pv3);
;     __syncthreads();
;     ATT_ISSUE((kt < kt_hi) ? kt + 1 : kt);
;     f32x4 sc[8];
;     float mx = -INFINITY;
; #pragma unroll
;     for (int t8 = 0; t8 < 8; ++t8) {
;       f32x4 a = f32x4{0.f, 0.f, 0.f, 0.f};
; #pragma unroll
;       for (int kk = 0; kk < 4; ++kk) {
;         bf16x8 kf = *(const bf16x8*)(Ks + (t8 * 16 + fr) * LDP + kk * 32 + fq * 8);
;         a = __builtin_amdgcn_mfma_f32_16x16x32_bf16(kf, qf[kk], a, 0, 0, 0);
;       }
; #pragma unroll
;       for (int j = 0; j < 4; ++j) {
;         const int rel = (kt - 1) * 128 + t8 * 16 + fq * 4 + j - qi;
;         const bool ok = (rel >= -128) && (rel <= 128);
;         const int ri = ok ? rel + 128 : 0;
;         const float v = ok ? (a[j] * scale + fb[ri]) : -INFINITY;
;         a[j] = v;
;         mx = fmaxf(mx, v);
;       }
;       sc[t8] = a;
.LBB0_560:
	s_bitcmp1_b32 s8, 0
	s_cselect_b32 s0, 0x11800, 0
	s_add_i32 s9, s0, 32
	s_cmp_ge_u32 s8, s4
	s_mov_b32 s2, s8
	v_add3_u32 v80, s9, v101, v88
	s_cselect_b64 s[0:1], -1, 0
	s_add_i32 s8, s8, 1
	s_waitcnt vmcnt(7)
	ds_write_b128 v80, v[16:19]
	v_add3_u32 v16, s9, v102, v88
	s_cmp_lt_u32 s2, s4
	s_waitcnt vmcnt(6)
	ds_write_b128 v16, v[20:23] offset:34816
	v_add3_u32 v16, s9, v103, v88
	s_cselect_b32 s2, s8, s2
	s_waitcnt vmcnt(5)
	ds_write_b128 v16, v[24:27]
	v_add3_u32 v16, s9, v104, v88
	s_add_i32 s2, s2, s7
	s_waitcnt vmcnt(4)
	ds_write_b128 v16, v[28:31] offset:34816
	v_add3_u32 v16, s9, v105, v88
	s_ashr_i32 s3, s2, 31
	s_waitcnt vmcnt(3)
	ds_write_b128 v16, v[32:35]
	v_add3_u32 v16, s9, v106, v88
	s_lshl_b64 s[2:3], s[2:3], 7
	s_waitcnt vmcnt(2)
	ds_write_b128 v16, v[36:39] offset:34816
	v_add3_u32 v16, s9, v107, v88
	s_add_u32 s2, s2, s5
	s_waitcnt vmcnt(1)
	ds_write_b128 v16, v[40:43]
	v_add3_u32 v16, s9, v108, v88
	s_addc_u32 s3, s3, s6
	s_waitcnt vmcnt(0)
	ds_write_b128 v16, v[44:47] offset:34816
	v_lshl_add_u64 v[16:17], s[2:3], 0, v[86:87]
	v_lshlrev_b64 v[16:17], 10, v[16:17]
	v_add_u32_e32 v28, s9, v144
	v_lshl_add_u64 v[18:19], v[96:97], 0, v[16:17]
	v_lshl_add_u64 v[20:21], v[98:99], 0, v[16:17]
	v_add_u32_e32 v126, v28, v111
	s_waitcnt lgkmcnt(0)
	s_barrier
	ds_read_b32 v210, v114
	ds_read_b32 v211, v114 offset:4
	ds_read_b32 v212, v114 offset:8
	ds_read_b32 v213, v114 offset:12
	v_mov_b32_e32 v214, 0xff800000
	global_load_dwordx4 v[16:19], v[18:19], off
	s_nop 0
	global_load_dwordx4 v[20:23], v[20:21], off
	ds_read_b128 v[32:35], v126
	v_lshl_add_u64 v[24:25], s[2:3], 0, v[90:91]
	v_lshlrev_b64 v[24:25], 10, v[24:25]
	v_lshl_add_u64 v[26:27], v[96:97], 0, v[24:25]
	v_lshl_add_u64 v[28:29], v[98:99], 0, v[24:25]
	global_load_dwordx4 v[24:27], v[26:27], off
	s_nop 0
	global_load_dwordx4 v[28:31], v[28:29], off
	ds_read_b128 v[40:43], v126 offset:64
	ds_read_b128 v[80:83], v126 offset:128
	s_waitcnt lgkmcnt(2)
	v_mfma_f32_16x16x32_bf16 v[44:47], v[32:35], v[0:3], 0
	v_lshl_add_u64 v[36:37], s[2:3], 0, v[92:93]
	v_lshl_add_u64 v[118:119], s[2:3], 0, v[94:95]
	v_lshlrev_b64 v[36:37], 10, v[36:37]
	s_waitcnt lgkmcnt(1)
	v_mfma_f32_16x16x32_bf16 v[40:43], v[40:43], v[4:7], v[44:47]
	v_lshlrev_b64 v[118:119], 10, v[118:119]
	v_lshl_add_u64 v[38:39], v[96:97], 0, v[36:37]
	v_lshl_add_u64 v[36:37], v[98:99], 0, v[36:37]
	v_lshl_add_u64 v[44:45], v[96:97], 0, v[118:119]
	v_lshl_add_u64 v[46:47], v[98:99], 0, v[118:119]
	global_load_dwordx4 v[32:35], v[38:39], off
	s_nop 0
	global_load_dwordx4 v[36:39], v[36:37], off
	ds_read_b128 v[118:121], v126 offset:192
	s_waitcnt lgkmcnt(1)
	v_mfma_f32_16x16x32_bf16 v[80:83], v[80:83], v[8:11], v[40:43]
	s_nop 2
	global_load_dwordx4 v[40:43], v[44:45], off
	s_nop 0
	global_load_dwordx4 v[44:47], v[46:47], off
	v_cmp_gt_u32_e32 vcc, s97, v113
	s_waitcnt lgkmcnt(0)
	v_mfma_f32_16x16x32_bf16 v[80:83], v[118:121], v[12:15], v[80:83]
	v_mov_b32_e32 v118, 0xff800000
	v_mov_b32_e32 v121, 0xff800000
	s_nop 3
	s_nop 1
	v_fmac_f32_e32 v210, 0x3db504f3, v80
	s_nop 0
	v_cndmask_b32_e32 v121, v214, v210, vcc
	s_nop 2
	v_add_u32_e32 v80, 1, v113
	v_cmp_gt_u32_e32 vcc, s97, v80
	v_fmac_f32_e32 v211, 0x3db504f3, v81
	s_nop 0
	v_cndmask_b32_e32 v118, v214, v211, vcc
	v_add_u32_e32 v80, 2, v113
	v_cmp_gt_u32_e32 vcc, s97, v80
	v_mov_b32_e32 v119, 0xff800000
	v_mov_b32_e32 v124, 0xff800000
	v_fmac_f32_e32 v212, 0x3db504f3, v82
	s_nop 0
	v_cndmask_b32_e32 v124, v214, v212, vcc
	v_add_u32_e32 v80, 3, v113
	v_cmp_gt_u32_e32 vcc, s97, v80
	v_fmac_f32_e32 v213, 0x3db504f3, v83
	s_nop 0
	v_cndmask_b32_e32 v119, v214, v213, vcc
	ds_read_b32 v210, v114 offset:64
	ds_read_b32 v211, v114 offset:68
	ds_read_b32 v212, v114 offset:72
	ds_read_b32 v213, v114 offset:76
	ds_read_b128 v[80:83], v126 offset:4352
	ds_read_b128 v[128:131], v126 offset:4416
	v_add_u32_e32 v120, 16, v113
	v_cmp_gt_u32_e32 vcc, s97, v120
	v_mov_b32_e32 v120, 0xff800000
	v_mov_b32_e32 v122, 0xff800000
	s_waitcnt lgkmcnt(1)
	v_mfma_f32_16x16x32_bf16 v[80:83], v[80:83], v[0:3], 0
	s_waitcnt lgkmcnt(0)
	v_mfma_f32_16x16x32_bf16 v[80:83], v[128:131], v[4:7], v[80:83]
	ds_read_b128 v[128:131], v126 offset:4480
	s_waitcnt lgkmcnt(0)
	v_mfma_f32_16x16x32_bf16 v[80:83], v[128:131], v[8:11], v[80:83]
	ds_read_b128 v[128:131], v126 offset:4544
	s_waitcnt lgkmcnt(0)
	v_mfma_f32_16x16x32_bf16 v[80:83], v[128:131], v[12:15], v[80:83]
	s_nop 3
	s_nop 3
	v_fmac_f32_e32 v210, 0x3db504f3, v80
	s_nop 0
	v_cndmask_b32_e32 v122, v214, v210, vcc
	s_nop 4
	v_add_u32_e32 v80, 17, v113
	v_cmp_gt_u32_e32 vcc, s97, v80
	v_fmac_f32_e32 v211, 0x3db504f3, v81
	s_nop 0
	v_cndmask_b32_e32 v120, v214, v211, vcc
	v_add_u32_e32 v80, 18, v113
	v_cmp_gt_u32_e32 vcc, s97, v80
	v_mov_b32_e32 v123, 0xff800000
	v_mov_b32_e32 v125, 0xff800000
	v_fmac_f32_e32 v212, 0x3db504f3, v82
	s_nop 0
	v_cndmask_b32_e32 v125, v214, v212, vcc
	v_add_u32_e32 v80, 19, v113
	v_cmp_gt_u32_e32 vcc, s97, v80
	v_fmac_f32_e32 v213, 0x3db504f3, v83
	s_nop 0
	v_cndmask_b32_e32 v123, v214, v213, vcc
	ds_read_b32 v210, v114 offset:128
	ds_read_b32 v211, v114 offset:132
	ds_read_b32 v212, v114 offset:136
	ds_read_b32 v213, v114 offset:140
	ds_read_b128 v[80:83], v126 offset:8704
	ds_read_b128 v[128:131], v126 offset:8768
	v_add_u32_e32 v127, 32, v113
	v_cmp_gt_u32_e32 vcc, s97, v127
	v_mov_b32_e32 v127, 0xff800000
	s_waitcnt lgkmcnt(1)
	v_mfma_f32_16x16x32_bf16 v[80:83], v[80:83], v[0:3], 0
	s_waitcnt lgkmcnt(0)
	v_mfma_f32_16x16x32_bf16 v[80:83], v[128:131], v[4:7], v[80:83]
	ds_read_b128 v[128:131], v126 offset:8832
	s_waitcnt lgkmcnt(0)
	v_mfma_f32_16x16x32_bf16 v[80:83], v[128:131], v[8:11], v[80:83]
	ds_read_b128 v[128:131], v126 offset:8896
	s_waitcnt lgkmcnt(0)
; __device__ __forceinline__ void attn_item(const Params& P, const int pass, const int item, const int wvi) {
;     ...
;     for (int t8 = 0; t8 < 8; ++t8) {
;       f32x4 a = f32x4{0.f, 0.f, 0.f, 0.f};
; #pragma unroll
;       for (int kk = 0; kk < 4; ++kk) {
;         bf16x8 kf = *(const bf16x8*)(Ks + (t8 * 16 + fr) * LDP + kk * 32 + fq * 8);
;         a = __builtin_amdgcn_mfma_f32_16x16x32_bf16(kf, qf[kk], a, 0, 0, 0);
;       }
; #pragma unroll
;       for (int j = 0; j < 4; ++j) {
;         const int rel = (kt - 1) * 128 + t8 * 16 + fq * 4 + j - qi;
;         const bool ok = (rel >= -128) && (rel <= 128);
;         const int ri = ok ? rel + 128 : 0;
;         const float v = ok ? (a[j] * scale + fb[ri]) : -INFINITY;
;         a[j] = v;
;         mx = fmaxf(mx, v);
;       }
;       sc[t8] = a;
	v_mfma_f32_16x16x32_bf16 v[80:83], v[128:131], v[12:15], v[80:83]
	v_mov_b32_e32 v128, 0xff800000
	s_nop 3
	s_nop 2
	v_fmac_f32_e32 v210, 0x3db504f3, v80
	s_nop 0
	v_cndmask_b32_e32 v128, v214, v210, vcc
	s_nop 3
	v_add_u32_e32 v80, 33, v113
	v_cmp_gt_u32_e32 vcc, s97, v80
	v_fmac_f32_e32 v211, 0x3db504f3, v81
	s_nop 0
	v_cndmask_b32_e32 v127, v214, v211, vcc
	v_add_u32_e32 v80, 34, v113
	v_cmp_gt_u32_e32 vcc, s97, v80
	v_mov_b32_e32 v129, 0xff800000
	v_mov_b32_e32 v130, 0xff800000
	v_fmac_f32_e32 v212, 0x3db504f3, v82
	s_nop 0
	v_cndmask_b32_e32 v130, v214, v212, vcc
	v_add_u32_e32 v80, 35, v113
	v_cmp_gt_u32_e32 vcc, s97, v80
	v_fmac_f32_e32 v213, 0x3db504f3, v83
	s_nop 0
	v_cndmask_b32_e32 v129, v214, v213, vcc
	ds_read_b32 v210, v114 offset:192
	ds_read_b32 v211, v114 offset:196
	ds_read_b32 v212, v114 offset:200
	ds_read_b32 v213, v114 offset:204
	ds_read_b128 v[80:83], v126 offset:13056
	ds_read_b128 v[132:135], v126 offset:13120
	v_add_u32_e32 v131, 48, v113
	v_cmp_gt_u32_e32 vcc, s97, v131
	v_mov_b32_e32 v131, 0xff800000
	v_mov_b32_e32 v136, 0xff800000
	s_waitcnt lgkmcnt(1)
	v_mfma_f32_16x16x32_bf16 v[80:83], v[80:83], v[0:3], 0
	s_waitcnt lgkmcnt(0)
	v_mfma_f32_16x16x32_bf16 v[80:83], v[132:135], v[4:7], v[80:83]
	ds_read_b128 v[132:135], v126 offset:13184
	s_waitcnt lgkmcnt(0)
	v_mfma_f32_16x16x32_bf16 v[80:83], v[132:135], v[8:11], v[80:83]
	ds_read_b128 v[132:135], v126 offset:13248
	s_waitcnt lgkmcnt(0)
	v_mfma_f32_16x16x32_bf16 v[80:83], v[132:135], v[12:15], v[80:83]
	s_nop 3
	s_nop 3
	v_fmac_f32_e32 v210, 0x3db504f3, v80
	s_nop 0
	v_cndmask_b32_e32 v136, v214, v210, vcc
	s_nop 4
	v_add_u32_e32 v80, 49, v113
	v_cmp_gt_u32_e32 vcc, s97, v80
	v_fmac_f32_e32 v211, 0x3db504f3, v81
	s_nop 0
	v_cndmask_b32_e32 v131, v214, v211, vcc
	v_add_u32_e32 v80, 50, v113
	v_cmp_gt_u32_e32 vcc, s97, v80
	v_mov_b32_e32 v139, 0xff800000
	v_mov_b32_e32 v138, 0xff800000
	v_fmac_f32_e32 v212, 0x3db504f3, v82
	s_nop 0
	v_cndmask_b32_e32 v138, v214, v212, vcc
	v_add_u32_e32 v80, 51, v113
	v_cmp_gt_u32_e32 vcc, s97, v80
	v_fmac_f32_e32 v213, 0x3db504f3, v83
	s_nop 0
	v_cndmask_b32_e32 v139, v214, v213, vcc
	ds_read_b32 v210, v114 offset:256
	ds_read_b32 v211, v114 offset:260
	ds_read_b32 v212, v114 offset:264
	ds_read_b32 v213, v114 offset:268
	ds_read_b128 v[80:83], v126 offset:17408
	ds_read_b128 v[132:135], v126 offset:17472
	v_mov_b32_e32 v140, 0xff800000
	v_mov_b32_e32 v141, 0xff800000
	s_waitcnt lgkmcnt(1)
	v_mfma_f32_16x16x32_bf16 v[80:83], v[80:83], v[0:3], 0
	s_waitcnt lgkmcnt(0)
	v_mfma_f32_16x16x32_bf16 v[80:83], v[132:135], v[4:7], v[80:83]
	ds_read_b128 v[132:135], v126 offset:17536
	s_waitcnt lgkmcnt(0)
	v_mfma_f32_16x16x32_bf16 v[80:83], v[132:135], v[8:11], v[80:83]
	ds_read_b128 v[132:135], v126 offset:17600
	s_waitcnt lgkmcnt(0)
	v_mfma_f32_16x16x32_bf16 v[80:83], v[132:135], v[12:15], v[80:83]
	v_add_u32_e32 v132, 64, v113
	v_cmp_gt_u32_e32 vcc, s97, v132
	s_nop 3
	s_nop 1
	v_fmac_f32_e32 v210, 0x3db504f3, v80
	s_nop 0
	v_cndmask_b32_e32 v141, v214, v210, vcc
	s_nop 2
	v_add_u32_e32 v80, 0x41, v113
	v_cmp_gt_u32_e32 vcc, s97, v80
	v_fmac_f32_e32 v211, 0x3db504f3, v81
	s_nop 0
	v_cndmask_b32_e32 v140, v214, v211, vcc
	v_add_u32_e32 v80, 0x42, v113
	v_cmp_gt_u32_e32 vcc, s97, v80
	v_mov_b32_e32 v142, 0xff800000
	v_mov_b32_e32 v143, 0xff800000
	v_fmac_f32_e32 v212, 0x3db504f3, v82
	s_nop 0
	v_cndmask_b32_e32 v143, v214, v212, vcc
	v_add_u32_e32 v80, 0x43, v113
	v_cmp_gt_u32_e32 vcc, s97, v80
	v_fmac_f32_e32 v213, 0x3db504f3, v83
	s_nop 0
	v_cndmask_b32_e32 v142, v214, v213, vcc
	ds_read_b32 v210, v114 offset:320
	ds_read_b32 v211, v114 offset:324
	ds_read_b32 v212, v114 offset:328
	ds_read_b32 v213, v114 offset:332
	ds_read_b128 v[80:83], v126 offset:21760
	ds_read_b128 v[132:135], v126 offset:21824
	v_mov_b32_e32 v148, 0xff800000
	v_mov_b32_e32 v149, 0xff800000
	s_waitcnt lgkmcnt(1)
	v_mfma_f32_16x16x32_bf16 v[80:83], v[80:83], v[0:3], 0
	s_waitcnt lgkmcnt(0)
	v_mfma_f32_16x16x32_bf16 v[80:83], v[132:135], v[4:7], v[80:83]
	ds_read_b128 v[132:135], v126 offset:21888
	s_waitcnt lgkmcnt(0)
	v_mfma_f32_16x16x32_bf16 v[80:83], v[132:135], v[8:11], v[80:83]
	ds_read_b128 v[132:135], v126 offset:21952
	s_waitcnt lgkmcnt(0)
	v_mfma_f32_16x16x32_bf16 v[80:83], v[132:135], v[12:15], v[80:83]
	v_add_u32_e32 v132, 0x50, v113
	v_cmp_gt_u32_e32 vcc, s97, v132
	s_nop 3
	s_nop 1
	v_fmac_f32_e32 v210, 0x3db504f3, v80
	s_nop 0
	v_cndmask_b32_e32 v149, v214, v210, vcc
	s_nop 2
	v_add_u32_e32 v80, 0x51, v113
	v_cmp_gt_u32_e32 vcc, s97, v80
	v_fmac_f32_e32 v211, 0x3db504f3, v81
	s_nop 0
	v_cndmask_b32_e32 v148, v214, v211, vcc
	v_add_u32_e32 v80, 0x52, v113
	v_cmp_gt_u32_e32 vcc, s97, v80
	v_mov_b32_e32 v151, 0xff800000
	v_mov_b32_e32 v152, 0xff800000
	v_fmac_f32_e32 v212, 0x3db504f3, v82
	s_nop 0
	v_cndmask_b32_e32 v152, v214, v212, vcc
	v_add_u32_e32 v80, 0x53, v113
	v_cmp_gt_u32_e32 vcc, s97, v80
	v_fmac_f32_e32 v213, 0x3db504f3, v83
	s_nop 0
	v_cndmask_b32_e32 v151, v214, v213, vcc
	ds_read_b32 v210, v114 offset:384
	ds_read_b32 v211, v114 offset:388
	ds_read_b32 v212, v114 offset:392
	ds_read_b32 v213, v114 offset:396
	ds_read_b128 v[80:83], v126 offset:26112
	ds_read_b128 v[132:135], v126 offset:26176
	v_mov_b32_e32 v153, 0xff800000
	v_mov_b32_e32 v154, 0xff800000
	s_waitcnt lgkmcnt(1)
	v_mfma_f32_16x16x32_bf16 v[80:83], v[80:83], v[0:3], 0
	s_waitcnt lgkmcnt(0)
	v_mfma_f32_16x16x32_bf16 v[80:83], v[132:135], v[4:7], v[80:83]
	ds_read_b128 v[132:135], v126 offset:26240
	s_waitcnt lgkmcnt(0)
	v_mfma_f32_16x16x32_bf16 v[80:83], v[132:135], v[8:11], v[80:83]
	ds_read_b128 v[132:135], v126 offset:26304
	s_waitcnt lgkmcnt(0)
; __device__ __forceinline__ void attn_item(const Params& P, const int pass, const int item, const int wvi) {
;     ...
;     for (int t8 = 0; t8 < 8; ++t8) {
;       f32x4 a = f32x4{0.f, 0.f, 0.f, 0.f};
; #pragma unroll
;       for (int kk = 0; kk < 4; ++kk) {
;         bf16x8 kf = *(const bf16x8*)(Ks + (t8 * 16 + fr) * LDP + kk * 32 + fq * 8);
;         a = __builtin_amdgcn_mfma_f32_16x16x32_bf16(kf, qf[kk], a, 0, 0, 0);
;       }
; #pragma unroll
;       for (int j = 0; j < 4; ++j) {
;         const int rel = (kt - 1) * 128 + t8 * 16 + fq * 4 + j - qi;
;         const bool ok = (rel >= -128) && (rel <= 128);
;         const int ri = ok ? rel + 128 : 0;
;         const float v = ok ? (a[j] * scale + fb[ri]) : -INFINITY;
;         a[j] = v;
;         mx = fmaxf(mx, v);
;       }
;       sc[t8] = a;
;     }
;     mx = fmaxf(mx, shfl_src(mx, lane ^ 16));
;     mx = fmaxf(mx, shfl_src(mx, lane ^ 32));
;     const float mnew = fmaxf(mrun, mx);
;     const float alpha = __expf(mrun - mnew);
;     float psum = 0.f;
; #pragma unroll
;     for (int t8 = 0; t8 < 8; ++t8)
; #pragma unroll
;       for (int j = 0; j < 4; ++j) { const float pv = __expf(sc[t8][j] - mnew); sc[t8][j] = pv; psum += pv; }
	v_mfma_f32_16x16x32_bf16 v[80:83], v[132:135], v[12:15], v[80:83]
	v_add_u32_e32 v132, 0x60, v113
	v_cmp_gt_u32_e32 vcc, s97, v132
	s_nop 3
	s_nop 1
	v_fmac_f32_e32 v210, 0x3db504f3, v80
	s_nop 0
	v_cndmask_b32_e32 v154, v214, v210, vcc
	s_nop 2
	v_add_u32_e32 v80, 0x61, v113
	v_cmp_gt_u32_e32 vcc, s97, v80
	v_fmac_f32_e32 v211, 0x3db504f3, v81
	s_nop 0
	v_cndmask_b32_e32 v153, v214, v211, vcc
	v_add_u32_e32 v80, 0x62, v113
	v_cmp_gt_u32_e32 vcc, s97, v80
	v_mov_b32_e32 v155, 0xff800000
	v_mov_b32_e32 v156, 0xff800000
	v_fmac_f32_e32 v212, 0x3db504f3, v82
	s_nop 0
	v_cndmask_b32_e32 v156, v214, v212, vcc
	v_add_u32_e32 v80, 0x63, v113
	v_cmp_gt_u32_e32 vcc, s97, v80
	v_fmac_f32_e32 v213, 0x3db504f3, v83
	s_nop 0
	v_cndmask_b32_e32 v155, v214, v213, vcc
	ds_read_b32 v210, v114 offset:448
	ds_read_b32 v211, v114 offset:452
	ds_read_b32 v212, v114 offset:456
	ds_read_b32 v213, v114 offset:460
	ds_read_b128 v[80:83], v126 offset:30464
	ds_read_b128 v[132:135], v126 offset:30528
	v_mov_b32_e32 v157, 0xff800000
	v_mov_b32_e32 v158, 0xff800000
	s_waitcnt lgkmcnt(1)
	v_mfma_f32_16x16x32_bf16 v[80:83], v[80:83], v[0:3], 0
	s_waitcnt lgkmcnt(0)
	v_mfma_f32_16x16x32_bf16 v[80:83], v[132:135], v[4:7], v[80:83]
	ds_read_b128 v[132:135], v126 offset:30592
	s_waitcnt lgkmcnt(0)
	v_mfma_f32_16x16x32_bf16 v[80:83], v[132:135], v[8:11], v[80:83]
	ds_read_b128 v[132:135], v126 offset:30656
	v_add_u32_e32 v126, 0x70, v113
	v_cmp_gt_u32_e32 vcc, s97, v126
	s_waitcnt lgkmcnt(0)
	v_mfma_f32_16x16x32_bf16 v[80:83], v[132:135], v[12:15], v[80:83]
	s_nop 3
	s_nop 3
	v_fmac_f32_e32 v210, 0x3db504f3, v80
	s_nop 0
	v_cndmask_b32_e32 v158, v214, v210, vcc
	s_nop 4
	v_add_u32_e32 v80, 0x71, v113
	v_cmp_gt_u32_e32 vcc, s97, v80
	v_fmac_f32_e32 v211, 0x3db504f3, v81
	s_nop 0
	v_cndmask_b32_e32 v157, v214, v211, vcc
	v_add_u32_e32 v80, 0x72, v113
	v_cmp_gt_u32_e32 vcc, s97, v80
	v_mov_b32_e32 v80, 0xff800000
	v_mov_b32_e32 v159, 0xff800000
	v_fmac_f32_e32 v212, 0x3db504f3, v82
	s_nop 0
	v_cndmask_b32_e32 v159, v214, v212, vcc
	v_add_u32_e32 v81, 0x73, v113
	v_cmp_gt_u32_e32 vcc, s97, v81
	v_fmac_f32_e32 v213, 0x3db504f3, v83
	s_nop 0
	v_cndmask_b32_e32 v80, v214, v213, vcc
	s_mov_b32 s2, 0xff800000
	v_max3_f32 v81, v121, s2, v118
	v_max3_f32 v81, v81, v124, v119
	v_max3_f32 v81, v81, v122, v120
	v_max3_f32 v81, v81, v125, v123
	v_max3_f32 v81, v81, v128, v127
	v_max3_f32 v81, v81, v130, v129
	v_max3_f32 v81, v81, v136, v131
	v_max3_f32 v81, v81, v138, v139
	v_max3_f32 v81, v81, v141, v140
	v_max3_f32 v81, v81, v143, v142
	v_max3_f32 v81, v81, v149, v148
	v_max3_f32 v81, v81, v152, v151
	v_max3_f32 v81, v81, v154, v153
	v_max3_f32 v81, v81, v156, v155
	v_max3_f32 v81, v81, v158, v157
	v_max3_f32 v81, v81, v159, v80
	ds_bpermute_b32 v82, v109, v81
	v_add_u32_e32 v113, 0x80, v113
	v_add_u32_e32 v114, 0x200, v114
	s_andn2_b64 vcc, exec, s[0:1]
	s_waitcnt lgkmcnt(0)
	v_max_f32_e32 v82, v82, v82
	v_max_f32_e32 v81, v81, v82
	ds_bpermute_b32 v82, v110, v81
	s_waitcnt lgkmcnt(0)
	v_max3_f32 v81, v117, v81, v82
	v_sub_f32_e32 v82, v117, v81
	v_sub_f32_e32 v117, v118, v81
	v_mul_f32_e32 v117, 0x3fb8aa3b, v117
	v_exp_f32_e32 v147, v117
	v_sub_f32_e32 v117, v124, v81
	v_mul_f32_e32 v117, 0x3fb8aa3b, v117
	v_exp_f32_e32 v150, v117
	v_sub_f32_e32 v117, v119, v81
	v_mul_f32_e32 v117, 0x3fb8aa3b, v117
	v_exp_f32_e32 v164, v117
	v_sub_f32_e32 v117, v122, v81
	v_mul_f32_e32 v117, 0x3fb8aa3b, v117
	v_exp_f32_e32 v166, v117
	v_sub_f32_e32 v117, v120, v81
	v_mul_f32_e32 v117, 0x3fb8aa3b, v117
	v_exp_f32_e32 v172, v117
	v_sub_f32_e32 v117, v125, v81
	v_mul_f32_e32 v117, 0x3fb8aa3b, v117
	v_exp_f32_e32 v173, v117
	v_sub_f32_e32 v117, v123, v81
	v_mul_f32_e32 v117, 0x3fb8aa3b, v117
	v_exp_f32_e32 v174, v117
	v_sub_f32_e32 v117, v128, v81
	v_mul_f32_e32 v117, 0x3fb8aa3b, v117
	v_exp_f32_e32 v132, v117
	v_sub_f32_e32 v117, v127, v81
	v_mul_f32_e32 v117, 0x3fb8aa3b, v117
	v_exp_f32_e32 v133, v117
	v_sub_f32_e32 v117, v130, v81
	v_mul_f32_e32 v117, 0x3fb8aa3b, v117
	v_exp_f32_e32 v134, v117
	v_sub_f32_e32 v117, v129, v81
	v_sub_f32_e32 v83, v121, v81
	v_mul_f32_e32 v117, 0x3fb8aa3b, v117
	v_mul_f32_e32 v83, 0x3fb8aa3b, v83
	v_exp_f32_e32 v135, v117
	v_sub_f32_e32 v117, v136, v81
	v_exp_f32_e32 v146, v83
	v_mul_f32_e32 v117, 0x3fb8aa3b, v117
	v_exp_f32_e32 v136, v117
	v_sub_f32_e32 v117, v131, v81
	v_mul_f32_e32 v117, 0x3fb8aa3b, v117
	v_exp_f32_e32 v137, v117
	v_sub_f32_e32 v117, v138, v81
	v_add_f32_e32 v83, 0, v146
	v_mul_f32_e32 v117, 0x3fb8aa3b, v117
	v_add_f32_e32 v83, v147, v83
	v_exp_f32_e32 v138, v117
	v_sub_f32_e32 v117, v139, v81
	v_add_f32_e32 v83, v150, v83
	v_mul_f32_e32 v117, 0x3fb8aa3b, v117
	v_add_f32_e32 v83, v164, v83
	v_exp_f32_e32 v139, v117
	v_sub_f32_e32 v117, v141, v81
	v_add_f32_e32 v83, v166, v83
	v_mul_f32_e32 v117, 0x3fb8aa3b, v117
	v_add_f32_e32 v83, v172, v83
	v_exp_f32_e32 v124, v117
	v_sub_f32_e32 v117, v140, v81
	v_add_f32_e32 v83, v173, v83
	v_mul_f32_e32 v117, 0x3fb8aa3b, v117
	v_add_f32_e32 v83, v174, v83
	v_exp_f32_e32 v125, v117
	v_sub_f32_e32 v117, v143, v81
	v_add_f32_e32 v83, v132, v83
	v_mul_f32_e32 v117, 0x3fb8aa3b, v117
	v_add_f32_e32 v83, v133, v83
	v_exp_f32_e32 v126, v117
	v_sub_f32_e32 v117, v142, v81
	v_add_f32_e32 v83, v134, v83
	v_mul_f32_e32 v117, 0x3fb8aa3b, v117
	v_add_f32_e32 v83, v135, v83
	v_exp_f32_e32 v127, v117
	v_sub_f32_e32 v117, v149, v81
	v_add_f32_e32 v83, v136, v83
	v_mul_f32_e32 v117, 0x3fb8aa3b, v117
	v_add_f32_e32 v83, v137, v83
	v_exp_f32_e32 v128, v117
	v_sub_f32_e32 v117, v148, v81
	v_add_f32_e32 v83, v138, v83
	v_mul_f32_e32 v117, 0x3fb8aa3b, v117
	v_add_f32_e32 v83, v139, v83
	v_exp_f32_e32 v129, v117
	v_sub_f32_e32 v117, v152, v81
; __device__ __forceinline__ void attn_item(const Params& P, const int pass, const int item, const int wvi) {
;     ...
;     const float alpha = __expf(mrun - mnew);
;     float psum = 0.f;
; #pragma unroll
;     for (int t8 = 0; t8 < 8; ++t8)
; #pragma unroll
;       for (int j = 0; j < 4; ++j) { const float pv = __expf(sc[t8][j] - mnew); sc[t8][j] = pv; psum += pv; }
;     psum += shfl_src(psum, lane ^ 16);
;     psum += shfl_src(psum, lane ^ 32);
;     lrun = lrun * alpha + psum;
;     mrun = mnew;
; #pragma unroll
;     for (int d8 = 0; d8 < 8; ++d8)
; #pragma unroll
;       for (int j = 0; j < 4; ++j) oacc[d8][j] *= alpha;
; #pragma unroll
;     for (int kp = 0; kp < 4; ++kp) {
;       const bf16x8 pf = pack8(sc[2 * kp][0], sc[2 * kp][1], sc[2 * kp][2], sc[2 * kp][3],
;                               sc[2 * kp + 1][0], sc[2 * kp + 1][1], sc[2 * kp + 1][2], sc[2 * kp + 1][3]);
; #pragma unroll
;       for (int d8 = 0; d8 < 8; ++d8) {
;         const u16* va = Vs + (kp * 32 + fq * 4 + (fr >> 2)) * LDV + d8 * 16 + (fr & 3) * 4;
;         s16x4 v0 = ldtr(va), v1 = ldtr(va + 16 * LDV);
;         oacc[d8] = __builtin_amdgcn_mfma_f32_16x16x32_bf16(cat8(v0, v1), pf, oacc[d8], 0, 0, 0);
;       }
;     }
	v_add_f32_e32 v83, v124, v83
	v_mul_f32_e32 v117, 0x3fb8aa3b, v117
	v_add_f32_e32 v83, v125, v83
	v_exp_f32_e32 v130, v117
	v_sub_f32_e32 v117, v151, v81
	v_add_f32_e32 v83, v126, v83
	v_mul_f32_e32 v117, 0x3fb8aa3b, v117
	v_add_f32_e32 v83, v127, v83
	v_exp_f32_e32 v131, v117
	v_add_f32_e32 v83, v128, v83
	v_add_f32_e32 v83, v129, v83
	v_add_f32_e32 v83, v130, v83
	v_add_f32_e32 v117, v131, v83
	v_sub_f32_e32 v83, v154, v81
	v_mul_f32_e32 v83, 0x3fb8aa3b, v83
	v_exp_f32_e32 v83, v83
	v_sub_f32_e32 v80, v80, v81
	v_mul_f32_e32 v80, 0x3fb8aa3b, v80
	v_mul_f32_e32 v82, 0x3fb8aa3b, v82
	v_add_f32_e32 v118, v83, v117
	v_sub_f32_e32 v117, v153, v81
	v_mul_f32_e32 v117, 0x3fb8aa3b, v117
	v_exp_f32_e32 v117, v117
	s_nop 0
	v_add_f32_e32 v119, v117, v118
	v_sub_f32_e32 v118, v156, v81
	v_mul_f32_e32 v118, 0x3fb8aa3b, v118
	v_exp_f32_e32 v118, v118
	s_nop 0
	v_add_f32_e32 v120, v118, v119
	v_sub_f32_e32 v119, v155, v81
	v_mul_f32_e32 v119, 0x3fb8aa3b, v119
	v_exp_f32_e32 v119, v119
	s_nop 0
	v_add_f32_e32 v121, v119, v120
	v_sub_f32_e32 v120, v158, v81
	v_mul_f32_e32 v120, 0x3fb8aa3b, v120
	v_exp_f32_e32 v120, v120
	s_nop 0
	v_add_f32_e32 v122, v120, v121
	v_sub_f32_e32 v121, v157, v81
	v_mul_f32_e32 v121, 0x3fb8aa3b, v121
	v_exp_f32_e32 v121, v121
	s_nop 0
	v_add_f32_e32 v123, v121, v122
	v_sub_f32_e32 v122, v159, v81
	v_mul_f32_e32 v122, 0x3fb8aa3b, v122
	v_exp_f32_e32 v122, v122
	s_nop 0
	v_add_f32_e32 v140, v122, v123
	v_exp_f32_e32 v123, v80
	v_exp_f32_e32 v80, v82
	v_add_f32_e32 v140, v123, v140
	ds_bpermute_b32 v82, v109, v140
	v_pk_mul_f32 v[160:161], v[60:61], v[80:81] op_sel_hi:[1,0]
	v_pk_mul_f32 v[162:163], v[62:63], v[80:81] op_sel_hi:[1,0]
	v_pk_mul_f32 v[168:169], v[64:65], v[80:81] op_sel_hi:[1,0]
	v_pk_mul_f32 v[170:171], v[66:67], v[80:81] op_sel_hi:[1,0]
	s_waitcnt lgkmcnt(0)
	v_add_f32_e32 v82, v140, v82
	v_pk_mul_f32 v[140:141], v[48:49], v[80:81] op_sel_hi:[1,0]
	v_pk_mul_f32 v[48:49], v[76:77], v[80:81] op_sel_hi:[1,0]
	v_add3_u32 v77, s9, v115, v112
	ds_read_b64_tr_b16 v[62:63], v77 offset:39424
	ds_read_b64_tr_b16 v[60:61], v77 offset:34816
	ds_read_b64_tr_b16 v[64:65], v77 offset:34848
	ds_read_b64_tr_b16 v[66:67], v77 offset:39456
	ds_bpermute_b32 v148, v110, v82
	v_pk_mul_f32 v[142:143], v[50:51], v[80:81] op_sel_hi:[1,0]
	v_pk_mul_f32 v[152:153], v[56:57], v[80:81] op_sel_hi:[1,0]
	v_pk_mul_f32 v[154:155], v[58:59], v[80:81] op_sel_hi:[1,0]
	v_pk_mul_f32 v[156:157], v[52:53], v[80:81] op_sel_hi:[1,0]
	v_pk_mul_f32 v[158:159], v[54:55], v[80:81] op_sel_hi:[1,0]
	v_cvt_pk_bf16_f32 v52, v146, v147
	v_cvt_pk_bf16_f32 v53, v150, v164
	v_cvt_pk_bf16_f32 v54, v166, v172
	v_cvt_pk_bf16_f32 v55, v173, v174
	v_pk_mul_f32 v[56:57], v[72:73], v[80:81] op_sel_hi:[1,0]
	v_pk_mul_f32 v[58:59], v[74:75], v[80:81] op_sel_hi:[1,0]
	s_waitcnt lgkmcnt(0)
	v_add_f32_e32 v82, v82, v148
	v_mfma_f32_16x16x32_bf16 v[60:63], v[60:63], v[52:55], v[140:143]
	ds_read_b64_tr_b16 v[72:73], v77 offset:34880
	ds_read_b64_tr_b16 v[74:75], v77 offset:39488
	s_nop 0
	ds_read_b64_tr_b16 v[140:141], v77 offset:34912
	ds_read_b64_tr_b16 v[142:143], v77 offset:39520
	ds_read_b64_tr_b16 v[146:147], v77 offset:34944
	ds_read_b64_tr_b16 v[148:149], v77 offset:39552
	v_mfma_f32_16x16x32_bf16 v[64:67], v[64:67], v[52:55], v[152:155]
	ds_read_b64_tr_b16 v[150:151], v77 offset:34976
	s_nop 1
	ds_read_b64_tr_b16 v[152:153], v77 offset:39584
	v_pk_mul_f32 v[68:69], v[68:69], v[80:81] op_sel_hi:[1,0]
	v_pk_mul_f32 v[70:71], v[70:71], v[80:81] op_sel_hi:[1,0]
	v_pk_mul_f32 v[50:51], v[78:79], v[80:81] op_sel_hi:[1,0]
	s_waitcnt lgkmcnt(6)
	v_mfma_f32_16x16x32_bf16 v[72:75], v[72:75], v[52:55], v[156:159]
	v_add_u32_e32 v76, 0x8800, v77
	v_fmac_f32_e32 v82, v116, v80
	s_waitcnt lgkmcnt(0)
	v_mfma_f32_16x16x32_bf16 v[68:71], v[150:153], v[52:55], v[68:71]
	ds_read_b64_tr_b16 v[150:151], v77 offset:35008
	ds_read_b64_tr_b16 v[152:153], v77 offset:39616
	s_waitcnt lgkmcnt(0)
	v_mfma_f32_16x16x32_bf16 v[56:59], v[150:153], v[52:55], v[56:59]
	ds_read_b64_tr_b16 v[150:151], v77 offset:35040
	ds_read_b64_tr_b16 v[152:153], v77 offset:39648
	v_mfma_f32_16x16x32_bf16 v[140:143], v[140:143], v[52:55], v[160:163]
	v_mfma_f32_16x16x32_bf16 v[146:149], v[146:149], v[52:55], v[168:171]
	s_waitcnt lgkmcnt(0)
	v_mfma_f32_16x16x32_bf16 v[48:51], v[150:153], v[52:55], v[48:51]
	v_cvt_pk_bf16_f32 v52, v132, v133
	v_cvt_pk_bf16_f32 v53, v134, v135
	ds_read_b64_tr_b16 v[132:133], v77 offset:44032
	ds_read_b64_tr_b16 v[134:135], v77 offset:48640
	v_cvt_pk_bf16_f32 v54, v136, v137
	v_cvt_pk_bf16_f32 v55, v138, v139
	s_waitcnt lgkmcnt(0)
; __device__ __forceinline__ void attn_item(const Params& P, const int pass, const int item, const int wvi) {
;     ...
; #pragma unroll
;     for (int kp = 0; kp < 4; ++kp) {
;       const bf16x8 pf = pack8(sc[2 * kp][0], sc[2 * kp][1], sc[2 * kp][2], sc[2 * kp][3],
;                               sc[2 * kp + 1][0], sc[2 * kp + 1][1], sc[2 * kp + 1][2], sc[2 * kp + 1][3]);
; #pragma unroll
;       for (int d8 = 0; d8 < 8; ++d8) {
;         const u16* va = Vs + (kp * 32 + fq * 4 + (fr >> 2)) * LDV + d8 * 16 + (fr & 3) * 4;
;         s16x4 v0 = ldtr(va), v1 = ldtr(va + 16 * LDV);
;         oacc[d8] = __builtin_amdgcn_mfma_f32_16x16x32_bf16(cat8(v0, v1), pf, oacc[d8], 0, 0, 0);
;       }
;     }
;   }
	s_nop 0
	v_mfma_f32_16x16x32_bf16 v[60:63], v[132:135], v[52:55], v[60:63]
	ds_read_b64_tr_b16 v[132:133], v77 offset:44064
	ds_read_b64_tr_b16 v[134:135], v77 offset:48672
	s_waitcnt lgkmcnt(0)
	v_mfma_f32_16x16x32_bf16 v[64:67], v[132:135], v[52:55], v[64:67]
	ds_read_b64_tr_b16 v[132:133], v77 offset:44096
	ds_read_b64_tr_b16 v[134:135], v77 offset:48704
	s_waitcnt lgkmcnt(0)
	v_mfma_f32_16x16x32_bf16 v[72:75], v[132:135], v[52:55], v[72:75]
	ds_read_b64_tr_b16 v[132:133], v77 offset:44128
	ds_read_b64_tr_b16 v[134:135], v77 offset:48736
	ds_read_b64_tr_b16 v[136:137], v77 offset:44160
	ds_read_b64_tr_b16 v[138:139], v77 offset:48768
	s_waitcnt lgkmcnt(2)
	v_mfma_f32_16x16x32_bf16 v[132:135], v[132:135], v[52:55], v[140:143]
	s_nop 2
	ds_read_b64_tr_b16 v[140:141], v77 offset:44192
	ds_read_b64_tr_b16 v[142:143], v77 offset:48800
	s_waitcnt lgkmcnt(0)
	v_mfma_f32_16x16x32_bf16 v[68:71], v[140:143], v[52:55], v[68:71]
	ds_read_b64_tr_b16 v[140:141], v77 offset:44224
	ds_read_b64_tr_b16 v[142:143], v77 offset:48832
	s_waitcnt lgkmcnt(0)
	v_mfma_f32_16x16x32_bf16 v[56:59], v[140:143], v[52:55], v[56:59]
	ds_read_b64_tr_b16 v[140:141], v77 offset:44256
	ds_read_b64_tr_b16 v[142:143], v77 offset:48864
	v_mfma_f32_16x16x32_bf16 v[136:139], v[136:139], v[52:55], v[146:149]
	s_waitcnt lgkmcnt(0)
	v_mfma_f32_16x16x32_bf16 v[48:51], v[140:143], v[52:55], v[48:51]
	v_cvt_pk_bf16_f32 v52, v124, v125
	v_cvt_pk_bf16_f32 v53, v126, v127
	ds_read_b64_tr_b16 v[124:125], v77 offset:53248
	ds_read_b64_tr_b16 v[126:127], v77 offset:57856
	v_cvt_pk_bf16_f32 v54, v128, v129
	v_cvt_pk_bf16_f32 v55, v130, v131
	v_cvt_pk_bf16_f32 v140, v83, v117
	v_cvt_pk_bf16_f32 v141, v118, v119
	s_waitcnt lgkmcnt(0)
	v_mfma_f32_16x16x32_bf16 v[60:63], v[124:127], v[52:55], v[60:63]
	ds_read_b64_tr_b16 v[124:125], v77 offset:53280
	ds_read_b64_tr_b16 v[126:127], v77 offset:57888
	v_cvt_pk_bf16_f32 v142, v120, v121
	v_cvt_pk_bf16_f32 v143, v122, v123
	s_waitcnt lgkmcnt(0)
	v_mfma_f32_16x16x32_bf16 v[64:67], v[124:127], v[52:55], v[64:67]
	ds_read_b64_tr_b16 v[124:125], v77 offset:53312
	ds_read_b64_tr_b16 v[126:127], v77 offset:57920
	s_waitcnt lgkmcnt(0)
	v_mfma_f32_16x16x32_bf16 v[72:75], v[124:127], v[52:55], v[72:75]
	ds_read_b64_tr_b16 v[124:125], v77 offset:53344
	ds_read_b64_tr_b16 v[126:127], v77 offset:57952
	ds_read_b64_tr_b16 v[128:129], v77 offset:53376
	ds_read_b64_tr_b16 v[130:131], v77 offset:57984
	s_waitcnt lgkmcnt(2)
	v_mfma_f32_16x16x32_bf16 v[124:127], v[124:127], v[52:55], v[132:135]
	s_nop 2
	ds_read_b64_tr_b16 v[132:133], v77 offset:53408
	ds_read_b64_tr_b16 v[134:135], v77 offset:58016
	s_waitcnt lgkmcnt(0)
	v_mfma_f32_16x16x32_bf16 v[68:71], v[132:135], v[52:55], v[68:71]
	ds_read_b64_tr_b16 v[132:133], v77 offset:53440
	ds_read_b64_tr_b16 v[134:135], v77 offset:58048
	s_waitcnt lgkmcnt(0)
	v_mfma_f32_16x16x32_bf16 v[132:135], v[132:135], v[52:55], v[56:59]
	s_nop 2
	ds_read_b64_tr_b16 v[56:57], v77 offset:53472
	ds_read_b64_tr_b16 v[58:59], v77 offset:58080
	v_mfma_f32_16x16x32_bf16 v[128:131], v[128:131], v[52:55], v[136:139]
	s_waitcnt lgkmcnt(0)
	v_mfma_f32_16x16x32_bf16 v[136:139], v[56:59], v[52:55], v[48:51]
	s_nop 2
	ds_read_b64_tr_b16 v[48:49], v77 offset:62464
	ds_read_b64_tr_b16 v[50:51], v76 offset:32256
	ds_read_b64_tr_b16 v[54:55], v76 offset:32288
	ds_read_b64_tr_b16 v[52:53], v77 offset:62496
	s_waitcnt lgkmcnt(0)
	v_mfma_f32_16x16x32_bf16 v[56:59], v[52:55], v[140:143], v[64:67]
	ds_read_b64_tr_b16 v[52:53], v77 offset:62528
	ds_read_b64_tr_b16 v[54:55], v76 offset:32320
	v_mfma_f32_16x16x32_bf16 v[48:51], v[48:51], v[140:143], v[60:63]
	s_nop 2
	ds_read_b64_tr_b16 v[60:61], v77 offset:62560
	ds_read_b64_tr_b16 v[62:63], v76 offset:32352
	ds_read_b64_tr_b16 v[64:65], v77 offset:62592
	ds_read_b64_tr_b16 v[66:67], v76 offset:32384
	s_waitcnt lgkmcnt(4)
	v_mfma_f32_16x16x32_bf16 v[52:55], v[52:55], v[140:143], v[72:75]
	s_nop 2
	ds_read_b64_tr_b16 v[72:73], v77 offset:62624
	ds_read_b64_tr_b16 v[74:75], v76 offset:32416
	s_waitcnt lgkmcnt(0)
	v_mfma_f32_16x16x32_bf16 v[68:71], v[72:75], v[140:143], v[68:71]
	ds_read_b64_tr_b16 v[72:73], v77 offset:62656
	ds_read_b64_tr_b16 v[74:75], v76 offset:32448
	ds_read_b64_tr_b16 v[118:119], v77 offset:62688
	ds_read_b64_tr_b16 v[120:121], v76 offset:32480
	v_mfma_f32_16x16x32_bf16 v[60:63], v[60:63], v[140:143], v[124:127]
	v_mfma_f32_16x16x32_bf16 v[64:67], v[64:67], v[140:143], v[128:131]
	s_waitcnt lgkmcnt(2)
	v_mfma_f32_16x16x32_bf16 v[72:75], v[72:75], v[140:143], v[132:135]
	s_waitcnt lgkmcnt(0)
	v_mfma_f32_16x16x32_bf16 v[76:79], v[118:121], v[140:143], v[136:139]
	s_cbranch_vccz .LBB0_626
	v_mov_b32_e32 v117, v81
	v_mov_b32_e32 v116, v82
	s_branch .LBB0_560
